# attention unit epilogue: the 8 staged output rows read from LDS up front, then 8 stores (no per-row LDS round trip)
# baseline (speedup 1.0000x reference)
.Lat_drain:
	v_add_f32_e32 v247, v247, v128
	v_add_f32_e32 v247, v247, v129
	v_add_f32_e32 v247, v247, v130
	v_add_f32_e32 v247, v247, v131
	v_cvt_pk_bf16_f32 v176, v128, v129
	v_cvt_pk_bf16_f32 v177, v130, v131
	v_add_f32_e32 v247, v247, v132
	v_add_f32_e32 v247, v247, v133
	v_add_f32_e32 v247, v247, v134
	v_add_f32_e32 v247, v247, v135
	v_cvt_pk_bf16_f32 v178, v132, v133
	v_cvt_pk_bf16_f32 v179, v134, v135
	v_add_f32_e32 v247, v247, v136
	v_add_f32_e32 v247, v247, v137
	v_add_f32_e32 v247, v247, v138
	v_add_f32_e32 v247, v247, v139
	v_cvt_pk_bf16_f32 v180, v136, v137
	v_cvt_pk_bf16_f32 v181, v138, v139
	v_add_f32_e32 v247, v247, v140
	v_add_f32_e32 v247, v247, v141
	v_add_f32_e32 v247, v247, v142
	v_add_f32_e32 v247, v247, v143
	v_cvt_pk_bf16_f32 v182, v140, v141
	v_cvt_pk_bf16_f32 v183, v142, v143
	v_add_f32_e32 v247, v247, v144
	v_add_f32_e32 v247, v247, v145
	v_add_f32_e32 v247, v247, v146
	v_add_f32_e32 v247, v247, v147
	v_cvt_pk_bf16_f32 v184, v144, v145
	v_cvt_pk_bf16_f32 v185, v146, v147
	v_add_f32_e32 v247, v247, v148
	v_add_f32_e32 v247, v247, v149
	v_add_f32_e32 v247, v247, v150
	v_add_f32_e32 v247, v247, v151
	v_cvt_pk_bf16_f32 v186, v148, v149
	v_cvt_pk_bf16_f32 v187, v150, v151
	v_add_f32_e32 v247, v247, v152
	v_add_f32_e32 v247, v247, v153
	v_add_f32_e32 v247, v247, v154
	v_add_f32_e32 v247, v247, v155
	v_cvt_pk_bf16_f32 v188, v152, v153
	v_cvt_pk_bf16_f32 v189, v154, v155
	v_add_f32_e32 v247, v247, v156
	v_add_f32_e32 v247, v247, v157
	v_add_f32_e32 v247, v247, v158
	v_add_f32_e32 v247, v247, v159
	v_cvt_pk_bf16_f32 v190, v156, v157
	v_cvt_pk_bf16_f32 v191, v158, v159
	s_lshl_b32 s60, s56, 1
	v_add_u32_e32 v250, s60, v245
	ds_read_b64_tr_b16 v[192:193], v250 offset:0
	ds_read_b64_tr_b16 v[194:195], v250 offset:512
	ds_read_b64_tr_b16 v[196:197], v250 offset:4096
	ds_read_b64_tr_b16 v[198:199], v250 offset:4608
	ds_read_b64_tr_b16 v[200:201], v250 offset:8192
	ds_read_b64_tr_b16 v[202:203], v250 offset:8704
	ds_read_b64_tr_b16 v[204:205], v250 offset:12288
	ds_read_b64_tr_b16 v[206:207], v250 offset:12800
	s_waitcnt lgkmcnt(6)
	v_mfma_f32_32x32x16_bf16 v[32:47], v[176:179], v[192:195], v[32:47]
	ds_read_b64_tr_b16 v[192:193], v250 offset:1024
	ds_read_b64_tr_b16 v[194:195], v250 offset:1536
	s_waitcnt lgkmcnt(6)
	v_mfma_f32_32x32x16_bf16 v[48:63], v[176:179], v[196:199], v[48:63]
	ds_read_b64_tr_b16 v[196:197], v250 offset:5120
	ds_read_b64_tr_b16 v[198:199], v250 offset:5632
	s_waitcnt lgkmcnt(6)
	v_mfma_f32_32x32x16_bf16 v[64:79], v[176:179], v[200:203], v[64:79]
	ds_read_b64_tr_b16 v[200:201], v250 offset:9216
	ds_read_b64_tr_b16 v[202:203], v250 offset:9728
	s_waitcnt lgkmcnt(6)
	v_mfma_f32_32x32x16_bf16 v[80:95], v[176:179], v[204:207], v[80:95]
	ds_read_b64_tr_b16 v[204:205], v250 offset:13312
	ds_read_b64_tr_b16 v[206:207], v250 offset:13824
	s_waitcnt lgkmcnt(6)
	v_mfma_f32_32x32x16_bf16 v[32:47], v[180:183], v[192:195], v[32:47]
	ds_read_b64_tr_b16 v[192:193], v250 offset:2048
	ds_read_b64_tr_b16 v[194:195], v250 offset:2560
	s_waitcnt lgkmcnt(6)
	v_mfma_f32_32x32x16_bf16 v[48:63], v[180:183], v[196:199], v[48:63]
	ds_read_b64_tr_b16 v[196:197], v250 offset:6144
	ds_read_b64_tr_b16 v[198:199], v250 offset:6656
	s_waitcnt lgkmcnt(6)
	v_mfma_f32_32x32x16_bf16 v[64:79], v[180:183], v[200:203], v[64:79]
	ds_read_b64_tr_b16 v[200:201], v250 offset:10240
	ds_read_b64_tr_b16 v[202:203], v250 offset:10752
	s_waitcnt lgkmcnt(6)
	v_mfma_f32_32x32x16_bf16 v[80:95], v[180:183], v[204:207], v[80:95]
	ds_read_b64_tr_b16 v[204:205], v250 offset:14336
	ds_read_b64_tr_b16 v[206:207], v250 offset:14848
	s_waitcnt lgkmcnt(6)
	v_mfma_f32_32x32x16_bf16 v[32:47], v[184:187], v[192:195], v[32:47]
	ds_read_b64_tr_b16 v[192:193], v250 offset:3072
	ds_read_b64_tr_b16 v[194:195], v250 offset:3584
	s_waitcnt lgkmcnt(6)
	v_mfma_f32_32x32x16_bf16 v[48:63], v[184:187], v[196:199], v[48:63]
	ds_read_b64_tr_b16 v[196:197], v250 offset:7168
	ds_read_b64_tr_b16 v[198:199], v250 offset:7680
	s_waitcnt lgkmcnt(6)
	v_mfma_f32_32x32x16_bf16 v[64:79], v[184:187], v[200:203], v[64:79]
	ds_read_b64_tr_b16 v[200:201], v250 offset:11264
	ds_read_b64_tr_b16 v[202:203], v250 offset:11776
	s_waitcnt lgkmcnt(6)
	v_mfma_f32_32x32x16_bf16 v[80:95], v[184:187], v[204:207], v[80:95]
	ds_read_b64_tr_b16 v[204:205], v250 offset:15360
	ds_read_b64_tr_b16 v[206:207], v250 offset:15872
	s_waitcnt lgkmcnt(6)
	v_mfma_f32_32x32x16_bf16 v[32:47], v[188:191], v[192:195], v[32:47]
	s_waitcnt lgkmcnt(4)
	v_mfma_f32_32x32x16_bf16 v[48:63], v[188:191], v[196:199], v[48:63]
	s_waitcnt lgkmcnt(2)
	v_mfma_f32_32x32x16_bf16 v[64:79], v[188:191], v[200:203], v[64:79]
	s_waitcnt lgkmcnt(0)
	v_mfma_f32_32x32x16_bf16 v[80:95], v[188:191], v[204:207], v[80:95]
	v_mov_b32_e32 v250, v247
	v_mov_b32_e32 v251, v247
	s_nop 1
	v_permlane32_swap_b32_e32 v250, v251
	v_add_f32_e32 v250, v250, v251
	s_waitcnt vmcnt(0) lgkmcnt(0)
	s_barrier
	v_and_b32_e32 v244, 31, v237
	v_lshl_add_u32 v244, v244, 2, v249
	v_cmp_eq_u32_e32 vcc, 0, v252
	s_and_saveexec_b64 s[60:61], vcc
	ds_write_b32 v244, v250 offset:128
	s_or_b64 exec, exec, s[60:61]
	s_waitcnt lgkmcnt(0)
	v_lshl_add_u32 v250, v252, 4, v249
	ds_read_b128 v[0:3], v250 offset:128
	ds_read_b128 v[4:7], v250 offset:160
	ds_read_b128 v[8:11], v250 offset:192
	ds_read_b128 v[12:15], v250 offset:224
	s_waitcnt lgkmcnt(0)
	v_rcp_f32_e32 v0, v0
	v_rcp_f32_e32 v1, v1
	v_rcp_f32_e32 v2, v2
	v_rcp_f32_e32 v3, v3
	v_rcp_f32_e32 v4, v4
	v_rcp_f32_e32 v5, v5
	v_rcp_f32_e32 v6, v6
	v_rcp_f32_e32 v7, v7
	v_rcp_f32_e32 v8, v8
	v_rcp_f32_e32 v9, v9
	v_rcp_f32_e32 v10, v10
	v_rcp_f32_e32 v11, v11
	v_rcp_f32_e32 v12, v12
	v_rcp_f32_e32 v13, v13
	v_rcp_f32_e32 v14, v14
	v_rcp_f32_e32 v15, v15
	s_nop 7
	s_nop 7
	s_lshl_b32 s60, s47, 13
	v_and_b32_e32 v250, 31, v237
	v_lshlrev_b32_e32 v250, 1, v250
	v_add_u32_e32 v250, s60, v250
	v_lshlrev_b32_e32 v251, 10, v252
	v_add_u32_e32 v250, v250, v251
	v_mul_f32_e32 v251, v32, v0
	v_cvt_pk_bf16_f32 v251, v251, v251
	ds_write_b16 v250, v251 offset:0
	v_mul_f32_e32 v251, v48, v0
	v_cvt_pk_bf16_f32 v251, v251, v251
	ds_write_b16 v250, v251 offset:64
	v_mul_f32_e32 v251, v64, v0
	v_cvt_pk_bf16_f32 v251, v251, v251
	ds_write_b16 v250, v251 offset:128
	v_mul_f32_e32 v251, v80, v0
	v_cvt_pk_bf16_f32 v251, v251, v251
	ds_write_b16 v250, v251 offset:192
	v_mul_f32_e32 v251, v33, v1
	v_cvt_pk_bf16_f32 v251, v251, v251
	ds_write_b16 v250, v251 offset:256
	v_mul_f32_e32 v251, v49, v1
	v_cvt_pk_bf16_f32 v251, v251, v251
	ds_write_b16 v250, v251 offset:320
	v_mul_f32_e32 v251, v65, v1
	v_cvt_pk_bf16_f32 v251, v251, v251
	ds_write_b16 v250, v251 offset:384
	v_mul_f32_e32 v251, v81, v1
	v_cvt_pk_bf16_f32 v251, v251, v251
	ds_write_b16 v250, v251 offset:448
	v_mul_f32_e32 v251, v34, v2
	v_cvt_pk_bf16_f32 v251, v251, v251
	ds_write_b16 v250, v251 offset:512
	v_mul_f32_e32 v251, v50, v2
	v_cvt_pk_bf16_f32 v251, v251, v251
	ds_write_b16 v250, v251 offset:576
	v_mul_f32_e32 v251, v66, v2
	v_cvt_pk_bf16_f32 v251, v251, v251
	ds_write_b16 v250, v251 offset:640
	v_mul_f32_e32 v251, v82, v2
	v_cvt_pk_bf16_f32 v251, v251, v251
	ds_write_b16 v250, v251 offset:704
	v_mul_f32_e32 v251, v35, v3
	v_cvt_pk_bf16_f32 v251, v251, v251
	ds_write_b16 v250, v251 offset:768
	v_mul_f32_e32 v251, v51, v3
	v_cvt_pk_bf16_f32 v251, v251, v251
	ds_write_b16 v250, v251 offset:832
	v_mul_f32_e32 v251, v67, v3
	v_cvt_pk_bf16_f32 v251, v251, v251
	ds_write_b16 v250, v251 offset:896
	v_mul_f32_e32 v251, v83, v3
	v_cvt_pk_bf16_f32 v251, v251, v251
	ds_write_b16 v250, v251 offset:960
	v_mul_f32_e32 v251, v36, v4
	v_cvt_pk_bf16_f32 v251, v251, v251
	ds_write_b16 v250, v251 offset:2048
	v_mul_f32_e32 v251, v52, v4
	v_cvt_pk_bf16_f32 v251, v251, v251
	ds_write_b16 v250, v251 offset:2112
	v_mul_f32_e32 v251, v68, v4
	v_cvt_pk_bf16_f32 v251, v251, v251
	ds_write_b16 v250, v251 offset:2176
	v_mul_f32_e32 v251, v84, v4
	v_cvt_pk_bf16_f32 v251, v251, v251
	ds_write_b16 v250, v251 offset:2240
	v_mul_f32_e32 v251, v37, v5
	v_cvt_pk_bf16_f32 v251, v251, v251
	ds_write_b16 v250, v251 offset:2304
	v_mul_f32_e32 v251, v53, v5
	v_cvt_pk_bf16_f32 v251, v251, v251
	ds_write_b16 v250, v251 offset:2368
	v_mul_f32_e32 v251, v69, v5
	v_cvt_pk_bf16_f32 v251, v251, v251
	ds_write_b16 v250, v251 offset:2432
	v_mul_f32_e32 v251, v85, v5
	v_cvt_pk_bf16_f32 v251, v251, v251
	ds_write_b16 v250, v251 offset:2496
	v_mul_f32_e32 v251, v38, v6
	v_cvt_pk_bf16_f32 v251, v251, v251
	ds_write_b16 v250, v251 offset:2560
	v_mul_f32_e32 v251, v54, v6
	v_cvt_pk_bf16_f32 v251, v251, v251
	ds_write_b16 v250, v251 offset:2624
	v_mul_f32_e32 v251, v70, v6
	v_cvt_pk_bf16_f32 v251, v251, v251
	ds_write_b16 v250, v251 offset:2688
	v_mul_f32_e32 v251, v86, v6
	v_cvt_pk_bf16_f32 v251, v251, v251
	ds_write_b16 v250, v251 offset:2752
	v_mul_f32_e32 v251, v39, v7
	v_cvt_pk_bf16_f32 v251, v251, v251
	ds_write_b16 v250, v251 offset:2816
	v_mul_f32_e32 v251, v55, v7
	v_cvt_pk_bf16_f32 v251, v251, v251
	ds_write_b16 v250, v251 offset:2880
	v_mul_f32_e32 v251, v71, v7
	v_cvt_pk_bf16_f32 v251, v251, v251
	ds_write_b16 v250, v251 offset:2944
	v_mul_f32_e32 v251, v87, v7
	v_cvt_pk_bf16_f32 v251, v251, v251
	ds_write_b16 v250, v251 offset:3008
	v_mul_f32_e32 v251, v40, v8
	v_cvt_pk_bf16_f32 v251, v251, v251
	ds_write_b16 v250, v251 offset:4096
	v_mul_f32_e32 v251, v56, v8
	v_cvt_pk_bf16_f32 v251, v251, v251
	ds_write_b16 v250, v251 offset:4160
	v_mul_f32_e32 v251, v72, v8
	v_cvt_pk_bf16_f32 v251, v251, v251
	ds_write_b16 v250, v251 offset:4224
	v_mul_f32_e32 v251, v88, v8
	v_cvt_pk_bf16_f32 v251, v251, v251
	ds_write_b16 v250, v251 offset:4288
	v_mul_f32_e32 v251, v41, v9
	v_cvt_pk_bf16_f32 v251, v251, v251
	ds_write_b16 v250, v251 offset:4352
	v_mul_f32_e32 v251, v57, v9
	v_cvt_pk_bf16_f32 v251, v251, v251
	ds_write_b16 v250, v251 offset:4416
	v_mul_f32_e32 v251, v73, v9
	v_cvt_pk_bf16_f32 v251, v251, v251
	ds_write_b16 v250, v251 offset:4480
	v_mul_f32_e32 v251, v89, v9
	v_cvt_pk_bf16_f32 v251, v251, v251
	ds_write_b16 v250, v251 offset:4544
	v_mul_f32_e32 v251, v42, v10
	v_cvt_pk_bf16_f32 v251, v251, v251
	ds_write_b16 v250, v251 offset:4608
	v_mul_f32_e32 v251, v58, v10
	v_cvt_pk_bf16_f32 v251, v251, v251
	ds_write_b16 v250, v251 offset:4672
	v_mul_f32_e32 v251, v74, v10
	v_cvt_pk_bf16_f32 v251, v251, v251
	ds_write_b16 v250, v251 offset:4736
	v_mul_f32_e32 v251, v90, v10
	v_cvt_pk_bf16_f32 v251, v251, v251
	ds_write_b16 v250, v251 offset:4800
	v_mul_f32_e32 v251, v43, v11
	v_cvt_pk_bf16_f32 v251, v251, v251
	ds_write_b16 v250, v251 offset:4864
	v_mul_f32_e32 v251, v59, v11
	v_cvt_pk_bf16_f32 v251, v251, v251
	ds_write_b16 v250, v251 offset:4928
	v_mul_f32_e32 v251, v75, v11
	v_cvt_pk_bf16_f32 v251, v251, v251
	ds_write_b16 v250, v251 offset:4992
	v_mul_f32_e32 v251, v91, v11
	v_cvt_pk_bf16_f32 v251, v251, v251
	ds_write_b16 v250, v251 offset:5056
	v_mul_f32_e32 v251, v44, v12
	v_cvt_pk_bf16_f32 v251, v251, v251
	ds_write_b16 v250, v251 offset:6144
	v_mul_f32_e32 v251, v60, v12
	v_cvt_pk_bf16_f32 v251, v251, v251
	ds_write_b16 v250, v251 offset:6208
	v_mul_f32_e32 v251, v76, v12
	v_cvt_pk_bf16_f32 v251, v251, v251
	ds_write_b16 v250, v251 offset:6272
	v_mul_f32_e32 v251, v92, v12
	v_cvt_pk_bf16_f32 v251, v251, v251
	ds_write_b16 v250, v251 offset:6336
	v_mul_f32_e32 v251, v45, v13
	v_cvt_pk_bf16_f32 v251, v251, v251
	ds_write_b16 v250, v251 offset:6400
	v_mul_f32_e32 v251, v61, v13
	v_cvt_pk_bf16_f32 v251, v251, v251
	ds_write_b16 v250, v251 offset:6464
	v_mul_f32_e32 v251, v77, v13
	v_cvt_pk_bf16_f32 v251, v251, v251
	ds_write_b16 v250, v251 offset:6528
	v_mul_f32_e32 v251, v93, v13
	v_cvt_pk_bf16_f32 v251, v251, v251
	ds_write_b16 v250, v251 offset:6592
	v_mul_f32_e32 v251, v46, v14
	v_cvt_pk_bf16_f32 v251, v251, v251
	ds_write_b16 v250, v251 offset:6656
	v_mul_f32_e32 v251, v62, v14
	v_cvt_pk_bf16_f32 v251, v251, v251
	ds_write_b16 v250, v251 offset:6720
	v_mul_f32_e32 v251, v78, v14
	v_cvt_pk_bf16_f32 v251, v251, v251
	ds_write_b16 v250, v251 offset:6784
	v_mul_f32_e32 v251, v94, v14
	v_cvt_pk_bf16_f32 v251, v251, v251
	ds_write_b16 v250, v251 offset:6848
	v_mul_f32_e32 v251, v47, v15
	v_cvt_pk_bf16_f32 v251, v251, v251
	ds_write_b16 v250, v251 offset:6912
	v_mul_f32_e32 v251, v63, v15
	v_cvt_pk_bf16_f32 v251, v251, v251
	ds_write_b16 v250, v251 offset:6976
	v_mul_f32_e32 v251, v79, v15
	v_cvt_pk_bf16_f32 v251, v251, v251
	ds_write_b16 v250, v251 offset:7040
	v_mul_f32_e32 v251, v95, v15
	v_cvt_pk_bf16_f32 v251, v251, v251
	ds_write_b16 v250, v251 offset:7104
	s_waitcnt lgkmcnt(0)
	v_lshrrev_b32_e32 v251, 4, v237
	v_and_b32_e32 v244, 15, v237
	v_lshlrev_b32_e32 v245, 8, v251
	v_lshl_or_b32 v245, v244, 4, v245
	v_add_u32_e32 v245, s60, v245
	v_lshlrev_b32_e32 v246, 11, v251
	v_lshl_or_b32 v246, v244, 4, v246
	ds_read_b128 v[16:19], v245 offset:0
	ds_read_b128 v[20:23], v245 offset:1024
	ds_read_b128 v[24:27], v245 offset:2048
	ds_read_b128 v[28:31], v245 offset:3072
	ds_read_b128 v[0:3], v245 offset:4096
	ds_read_b128 v[4:7], v245 offset:5120
	ds_read_b128 v[8:11], v245 offset:6144
	ds_read_b128 v[12:15], v245 offset:7168
	s_waitcnt lgkmcnt(7)
	global_store_dwordx4 v246, v[16:19], s[52:53]
	v_add_u32_e32 v246, 0x2000, v246
	s_waitcnt lgkmcnt(6)
	global_store_dwordx4 v246, v[20:23], s[52:53]
	v_add_u32_e32 v246, 0x2000, v246
	s_waitcnt lgkmcnt(5)
	global_store_dwordx4 v246, v[24:27], s[52:53]
	v_add_u32_e32 v246, 0x2000, v246
	s_waitcnt lgkmcnt(4)
	global_store_dwordx4 v246, v[28:31], s[52:53]
	v_add_u32_e32 v246, 0x2000, v246
	s_waitcnt lgkmcnt(3)
	global_store_dwordx4 v246, v[0:3], s[52:53]
	v_add_u32_e32 v246, 0x2000, v246
	s_waitcnt lgkmcnt(2)
	global_store_dwordx4 v246, v[4:7], s[52:53]
	v_add_u32_e32 v246, 0x2000, v246
	s_waitcnt lgkmcnt(1)
	global_store_dwordx4 v246, v[8:11], s[52:53]
	v_add_u32_e32 v246, 0x2000, v246
	s_waitcnt lgkmcnt(0)
	global_store_dwordx4 v246, v[12:15], s[52:53]
	s_waitcnt lgkmcnt(0)
	s_barrier
